# EpiResLn: the four LayerNorm statistics loads issued together (one wait) instead of four serialized round trips; plus x->f16 loop
# speedup vs baseline: 1.0017x; 1.0017x over previous
; #define PG8_LAS __attribute__((address_space(3)))
;     __device__ __forceinline__ void operator()(f32x4 (&acc)[2][2][4][2], const Unit& u, int wr, int wc, int fr, int fq) const {
;     ...
;         if (t < 256) { const size_t row = (size_t)u.pm * BM + t;
;             float s = 0.f, q = 0.f;
; #pragma unroll
;             for (int k4 = 0; k4 < 4; ++k4) { const unsigned long long w = __hip_atomic_load((const unsigned long long*)(st + row * 8 + 2 * k4), __ATOMIC_RELAXED, __HIP_MEMORY_SCOPE_AGENT);
;                 s += __uint_as_float((unsigned)w); q += __uint_as_float((unsigned)(w >> 32)); }
;             const float mean = s * (1.f / 1024.f), rstd = 1.f / sqrtf(q * (1.f / 1024.f) - mean * mean + eps);
;             *(PG8_LAS f32x2s*)(sl + 2 * t) = (f32x2s){mean, rstd}; }
.LBB0_375:
	s_or_b64 exec, exec, s[28:29]
	s_barrier
	s_and_saveexec_b64 s[28:29], s[4:5]
	s_cbranch_execz .LBB0_377
	s_lshl_b64 s[4:5], s[26:27], 13
	s_add_u32 s4, s54, s4
	s_addc_u32 s5, s72, s5
	s_waitcnt lgkmcnt(0)
	v_lshlrev_b64 v[2:3], 5, v[0:1]
	v_lshl_add_u64 v[2:3], s[4:5], 0, v[2:3]
	global_load_dwordx2 v[4:5], v[2:3], off sc1
	global_load_dwordx2 v[6:7], v[2:3], off offset:8 sc1
	global_load_dwordx2 v[246:247], v[2:3], off offset:16 sc1
	global_load_dwordx2 v[248:249], v[2:3], off offset:24 sc1
	s_mov_b32 s4, 0x3a800000
	v_lshl_add_u32 v0, v0, 3, 0
	v_add_u32_e32 v0, 0x20000, v0
	s_waitcnt vmcnt(0)
	v_add_f32_e32 v1, 0, v4
	v_add_f32_e32 v4, 0, v5
	v_add_f32_e32 v1, v1, v6
	v_add_f32_e32 v4, v4, v7
	v_add_f32_e32 v1, v1, v246
	v_add_f32_e32 v4, v4, v247
	v_add_f32_e32 v1, v1, v248
	v_mul_f32_e32 v2, 0x3a800000, v1
	v_add_f32_e32 v3, v4, v249
	v_mul_f32_e32 v1, v2, v2
	v_fma_f32 v1, v3, s4, -v1
	v_add_f32_e32 v1, 0x3727c5ac, v1
	s_mov_b32 s4, 0xf800000
	v_cmp_gt_f32_e32 vcc, s4, v1
	v_mul_f32_e32 v3, 0x4f800000, v1
	s_nop 0
	v_cndmask_b32_e32 v1, v1, v3, vcc
	v_sqrt_f32_e32 v3, v1
	s_nop 0
	v_add_u32_e32 v4, -1, v3
	v_fma_f32 v5, -v4, v3, v1
	v_cmp_ge_f32_e64 s[4:5], 0, v5
	v_add_u32_e32 v5, 1, v3
	s_nop 0
	v_cndmask_b32_e64 v4, v3, v4, s[4:5]
	v_fma_f32 v3, -v5, v3, v1
	v_cmp_lt_f32_e64 s[4:5], 0, v3
	s_nop 1
	v_cndmask_b32_e64 v3, v4, v5, s[4:5]
	v_mul_f32_e32 v4, 0x37800000, v3
	v_cndmask_b32_e32 v3, v3, v4, vcc
	v_cmp_class_f32_e32 vcc, v1, v203
	s_nop 1
	v_cndmask_b32_e32 v1, v3, v1, vcc
	v_div_scale_f32 v3, s[4:5], v1, v1, 1.0
	v_rcp_f32_e32 v4, v3
	s_nop 0
	v_fma_f32 v5, -v3, v4, 1.0
	v_fmac_f32_e32 v4, v5, v4
	v_div_scale_f32 v5, vcc, 1.0, v1, 1.0
	v_mul_f32_e32 v6, v5, v4
	v_fma_f32 v7, -v3, v6, v5
	v_fmac_f32_e32 v6, v7, v4
	v_fma_f32 v3, -v3, v6, v5
	v_div_fmas_f32 v3, v3, v4, v6
	v_div_fixup_f32 v3, v3, v1, 1.0
	ds_write_b64 v0, v[2:3]

; __global__ void __launch_bounds__(512, 2) fwd_kernel(Args args) {
	.amdhsa_kernel _Z10fwd_kernel4Args
		.amdhsa_group_segment_fixed_size 0
		.amdhsa_private_segment_fixed_size 0
		.amdhsa_kernarg_size 408
		.amdhsa_user_sgpr_count 2
		.amdhsa_user_sgpr_dispatch_ptr 0
		.amdhsa_user_sgpr_queue_ptr 0
		.amdhsa_user_sgpr_kernarg_segment_ptr 1
		.amdhsa_user_sgpr_dispatch_id 0
		.amdhsa_user_sgpr_kernarg_preload_length 0
		.amdhsa_user_sgpr_kernarg_preload_offset 0
		.amdhsa_user_sgpr_private_segment_size 0
		.amdhsa_uses_dynamic_stack 0
		.amdhsa_enable_private_segment 0
		.amdhsa_system_sgpr_workgroup_id_x 1
		.amdhsa_system_sgpr_workgroup_id_y 0
		.amdhsa_system_sgpr_workgroup_id_z 0
		.amdhsa_system_sgpr_workgroup_info 0
		.amdhsa_system_vgpr_workitem_id 2
		.amdhsa_next_free_vgpr 250
		.amdhsa_next_free_sgpr 100
		.amdhsa_accum_offset 252
		.amdhsa_reserve_vcc 1
		.amdhsa_float_round_mode_32 0
		.amdhsa_float_round_mode_16_64 0
		.amdhsa_float_denorm_mode_32 3
		.amdhsa_float_denorm_mode_16_64 3
		.amdhsa_dx10_clamp 1
		.amdhsa_ieee_mode 1
		.amdhsa_fp16_overflow 0
		.amdhsa_tg_split 0
		.amdhsa_exception_fp_ieee_invalid_op 0
		.amdhsa_exception_fp_denorm_src 0
		.amdhsa_exception_fp_ieee_div_zero 0
		.amdhsa_exception_fp_ieee_overflow 0
		.amdhsa_exception_fp_ieee_underflow 0
		.amdhsa_exception_fp_ieee_inexact 0
		.amdhsa_exception_int_div_zero 0
	.end_amdhsa_kernel

; __global__ void __launch_bounds__(512, 2) fwd_kernel(Args args) {
amdhsa.kernels:
  - .agpr_count:     0
    .args:
      - .offset:         0
        .size:           152
        .value_kind:     by_value
      - .offset:         152
        .size:           4
        .value_kind:     hidden_block_count_x
      - .offset:         156
        .size:           4
        .value_kind:     hidden_block_count_y
      - .offset:         160
        .size:           4
        .value_kind:     hidden_block_count_z
      - .offset:         164
        .size:           2
        .value_kind:     hidden_group_size_x
      - .offset:         166
        .size:           2
        .value_kind:     hidden_group_size_y
      - .offset:         168
        .size:           2
        .value_kind:     hidden_group_size_z
      - .offset:         170
        .size:           2
        .value_kind:     hidden_remainder_x
      - .offset:         172
        .size:           2
        .value_kind:     hidden_remainder_y
      - .offset:         174
        .size:           2
        .value_kind:     hidden_remainder_z
      - .offset:         192
        .size:           8
        .value_kind:     hidden_global_offset_x
      - .offset:         200
        .size:           8
        .value_kind:     hidden_global_offset_y
      - .offset:         208
        .size:           8
        .value_kind:     hidden_global_offset_z
      - .offset:         216
        .size:           2
        .value_kind:     hidden_grid_dims
      - .offset:         240
        .size:           8
        .value_kind:     hidden_multigrid_sync_arg
      - .offset:         272
        .size:           4
        .value_kind:     hidden_dynamic_lds_size
    .group_segment_fixed_size: 0
    .kernarg_segment_align: 8
    .kernarg_segment_size: 408
    .language:       OpenCL C
    .language_version:
      - 2
      - 0
    .max_flat_workgroup_size: 512
    .name:           _Z10fwd_kernel4Args
    .private_segment_fixed_size: 0
    .sgpr_count:     106
    .sgpr_spill_count: 143
    .symbol:         _Z10fwd_kernel4Args.kd
    .uniform_work_group_size: 1
    .uses_dynamic_stack: false
    .vgpr_count:     250
    .vgpr_spill_count: 0
    .wavefront_size: 64
